# same as previous (conv staging up-front loads), scratch SGPR renumbered
# speedup vs baseline: 1.0007x; 1.0007x over previous
; #define LAS __attribute__((address_space(3)))
; DI u32x4 pk8(f32x4 a, f32x4 b) { u32x4 w; w.x = pk2(a[0], a[1]); w.y = pk2(a[2], a[3]); w.z = pk2(b[0], b[1]); w.w = pk2(b[2], b[3]); return w; }
; DI void phase_conv(const Params& p, LAS unsigned char* lds) {
;     ...
;         for (int pr_ = wid; pr_ < (R + 30) / 2; pr_ += 8) {
;             u32x4 v0 = (u32x4){0u, 0u, 0u, 0u}, v1 = v0;
;             const int ta = t0 - 30 + 2 * pr_;
;             if (ta >= 0) { v0 = *(const u32x4*)(A0 + (rowbase + ta) * MW + c0); v1 = *(const u32x4*)(A0 + (rowbase + ta + 1) * MW + c0); }
;             else if (samp) { const f32x4* s0 = (const f32x4*)(cache_a + ((size_t)b * 30 + (30 + ta)) * MW + c0); const f32x4* s1 = s0 + MW / 4; v0 = pk8(s0[0], s0[1]); v1 = pk8(s1[0], s1[1]); }
;             u32x4 e0, e1;
;             e0.x = (v0.x & 0xffffu) | (v1.x << 16); e0.y = (v0.x >> 16) | (v1.x & 0xffff0000u); e0.z = (v0.y & 0xffffu) | (v1.y << 16); e0.w = (v0.y >> 16) | (v1.y & 0xffff0000u);
;             e1.x = (v0.z & 0xffffu) | (v1.z << 16); e1.y = (v0.z >> 16) | (v1.z & 0xffff0000u); e1.z = (v0.w & 0xffffu) | (v1.w << 16); e1.w = (v0.w >> 16) | (v1.w & 0xffff0000u);
;             *(LAS u32x4*)(lds + pr_ * 2048 + lane * 16) = e0; *(LAS u32x4*)(lds + pr_ * 2048 + 1024 + lane * 16) = e1;
;         }
.LBB0_415:
	s_mul_hi_u32 s69, s76, 0xf000
	s_andn2_b64 vcc, exec, s[0:1]
	s_mul_i32 s68, s76, 0xf000
	s_cbranch_vccnz .LBB0_424
	v_lshl_add_u64 v[10:11], v[42:43], 0, s[68:69]
	s_add_i32 s79, s33, s72
	v_mov_b32_e32 v12, v187
	s_mov_b32 s89, s8
	s_cmp_lt_i32 s79, 0
	s_cbranch_scc1 .LBB0_418
	s_sub_i32 s98, s78, s89
	s_add_i32 s98, s98, -1
	s_lshr_b32 s98, s98, 3
	s_lshl_b32 s99, s98, 4
	s_add_i32 s99, s99, s79
	s_mov_b32 s101, s79
	s_add_u32 s0, s62, s101
	s_addc_u32 s1, s63, 0
	s_lshl_b64 s[0:1], s[0:1], 10
	v_lshl_add_u64 v[18:19], v[38:39], 0, s[0:1]
	global_load_dwordx4 v[216:219], v[18:19], off
	global_load_dwordx4 v[220:223], v[18:19], off offset:1024
	s_add_i32 s101, s79, 16
	s_min_i32 s101, s101, s99
	s_add_u32 s0, s62, s101
	s_addc_u32 s1, s63, 0
	s_lshl_b64 s[0:1], s[0:1], 10
	v_lshl_add_u64 v[18:19], v[38:39], 0, s[0:1]
	global_load_dwordx4 v[224:227], v[18:19], off
	global_load_dwordx4 v[228:231], v[18:19], off offset:1024
	s_add_i32 s101, s79, 32
	s_min_i32 s101, s101, s99
	s_add_u32 s0, s62, s101
	s_addc_u32 s1, s63, 0
	s_lshl_b64 s[0:1], s[0:1], 10
	v_lshl_add_u64 v[18:19], v[38:39], 0, s[0:1]
	global_load_dwordx4 v[232:235], v[18:19], off
	global_load_dwordx4 v[236:239], v[18:19], off offset:1024
	s_add_i32 s101, s79, 48
	s_min_i32 s101, s101, s99
	s_add_u32 s0, s62, s101
	s_addc_u32 s1, s63, 0
	s_lshl_b64 s[0:1], s[0:1], 10
	v_lshl_add_u64 v[18:19], v[38:39], 0, s[0:1]
	global_load_dwordx4 v[240:243], v[18:19], off
	global_load_dwordx4 v[248:251], v[18:19], off offset:1024
	s_add_i32 s101, s79, 64
	s_min_i32 s101, s101, s99
	s_add_u32 s0, s62, s101
	s_addc_u32 s1, s63, 0
	s_lshl_b64 s[0:1], s[0:1], 10
	v_lshl_add_u64 v[18:19], v[38:39], 0, s[0:1]
	global_load_dwordx4 v[252:255], v[18:19], off
	global_load_dwordx4 v[2:5], v[18:19], off offset:1024
	s_add_i32 s101, s79, 80
	s_min_i32 s101, s101, s99
	s_add_u32 s0, s62, s101
	s_addc_u32 s1, s63, 0
	s_lshl_b64 s[0:1], s[0:1], 10
	v_lshl_add_u64 v[18:19], v[38:39], 0, s[0:1]
	global_load_dwordx4 v[6:9], v[18:19], off
	global_load_dwordx4 v[190:193], v[18:19], off offset:1024
	s_waitcnt vmcnt(10)
	v_lshlrev_b32_e32 v13, 16, v220
	v_and_or_b32 v14, v216, s85, v13
	v_lshrrev_b32_e32 v13, 16, v216
	v_and_or_b32 v15, v220, s86, v13
	v_lshlrev_b32_e32 v13, 16, v221
	v_and_or_b32 v16, v217, s85, v13
	v_lshrrev_b32_e32 v13, 16, v217
	v_and_or_b32 v17, v221, s86, v13
	v_lshlrev_b32_e32 v13, 16, v222
	v_and_or_b32 v20, v218, s85, v13
	v_lshrrev_b32_e32 v13, 16, v218
	v_and_or_b32 v21, v222, s86, v13
	v_lshlrev_b32_e32 v13, 16, v223
	v_and_or_b32 v22, v219, s85, v13
	v_lshrrev_b32_e32 v13, 16, v219
	v_and_or_b32 v23, v223, s86, v13
	ds_write_b128 v12, v[14:17]
	ds_write_b128 v12, v[20:23] offset:1024
	v_add_u32_e32 v12, 0x4000, v12
	s_cmp_eq_u32 s98, 0
	s_cbranch_scc1 .Lmy_cs_done
	s_waitcnt vmcnt(8)
	v_lshlrev_b32_e32 v13, 16, v228
	v_and_or_b32 v14, v224, s85, v13
	v_lshrrev_b32_e32 v13, 16, v224
	v_and_or_b32 v15, v228, s86, v13
	v_lshlrev_b32_e32 v13, 16, v229
	v_and_or_b32 v16, v225, s85, v13
	v_lshrrev_b32_e32 v13, 16, v225
	v_and_or_b32 v17, v229, s86, v13
	v_lshlrev_b32_e32 v13, 16, v230
	v_and_or_b32 v20, v226, s85, v13
	v_lshrrev_b32_e32 v13, 16, v226
	v_and_or_b32 v21, v230, s86, v13
	v_lshlrev_b32_e32 v13, 16, v231
	v_and_or_b32 v22, v227, s85, v13
	v_lshrrev_b32_e32 v13, 16, v227
	v_and_or_b32 v23, v231, s86, v13
	ds_write_b128 v12, v[14:17]
	ds_write_b128 v12, v[20:23] offset:1024
	v_add_u32_e32 v12, 0x4000, v12
	s_cmp_eq_u32 s98, 1
	s_cbranch_scc1 .Lmy_cs_done
	s_waitcnt vmcnt(6)
	v_lshlrev_b32_e32 v13, 16, v236
	v_and_or_b32 v14, v232, s85, v13
	v_lshrrev_b32_e32 v13, 16, v232
	v_and_or_b32 v15, v236, s86, v13
	v_lshlrev_b32_e32 v13, 16, v237
	v_and_or_b32 v16, v233, s85, v13
	v_lshrrev_b32_e32 v13, 16, v233
	v_and_or_b32 v17, v237, s86, v13
	v_lshlrev_b32_e32 v13, 16, v238
	v_and_or_b32 v20, v234, s85, v13
	v_lshrrev_b32_e32 v13, 16, v234
	v_and_or_b32 v21, v238, s86, v13
	v_lshlrev_b32_e32 v13, 16, v239
	v_and_or_b32 v22, v235, s85, v13
	v_lshrrev_b32_e32 v13, 16, v235
	v_and_or_b32 v23, v239, s86, v13
	ds_write_b128 v12, v[14:17]
	ds_write_b128 v12, v[20:23] offset:1024
	v_add_u32_e32 v12, 0x4000, v12
	s_cmp_eq_u32 s98, 2
	s_cbranch_scc1 .Lmy_cs_done
	s_waitcnt vmcnt(4)
	v_lshlrev_b32_e32 v13, 16, v248
	v_and_or_b32 v14, v240, s85, v13
	v_lshrrev_b32_e32 v13, 16, v240
	v_and_or_b32 v15, v248, s86, v13
	v_lshlrev_b32_e32 v13, 16, v249
	v_and_or_b32 v16, v241, s85, v13
	v_lshrrev_b32_e32 v13, 16, v241
	v_and_or_b32 v17, v249, s86, v13
	v_lshlrev_b32_e32 v13, 16, v250
	v_and_or_b32 v20, v242, s85, v13
	v_lshrrev_b32_e32 v13, 16, v242
	v_and_or_b32 v21, v250, s86, v13
	v_lshlrev_b32_e32 v13, 16, v251
	v_and_or_b32 v22, v243, s85, v13
	v_lshrrev_b32_e32 v13, 16, v243
	v_and_or_b32 v23, v251, s86, v13
	ds_write_b128 v12, v[14:17]
	ds_write_b128 v12, v[20:23] offset:1024
	v_add_u32_e32 v12, 0x4000, v12
	s_cmp_eq_u32 s98, 3
	s_cbranch_scc1 .Lmy_cs_done
	s_waitcnt vmcnt(2)
	v_lshlrev_b32_e32 v13, 16, v2
	v_and_or_b32 v14, v252, s85, v13
	v_lshrrev_b32_e32 v13, 16, v252
	v_and_or_b32 v15, v2, s86, v13
	v_lshlrev_b32_e32 v13, 16, v3
	v_and_or_b32 v16, v253, s85, v13
	v_lshrrev_b32_e32 v13, 16, v253
	v_and_or_b32 v17, v3, s86, v13
	v_lshlrev_b32_e32 v13, 16, v4
	v_and_or_b32 v20, v254, s85, v13
	v_lshrrev_b32_e32 v13, 16, v254
	v_and_or_b32 v21, v4, s86, v13
	v_lshlrev_b32_e32 v13, 16, v5
	v_and_or_b32 v22, v255, s85, v13
	v_lshrrev_b32_e32 v13, 16, v255
	v_and_or_b32 v23, v5, s86, v13
	ds_write_b128 v12, v[14:17]
	ds_write_b128 v12, v[20:23] offset:1024
	v_add_u32_e32 v12, 0x4000, v12
	s_cmp_eq_u32 s98, 4
	s_cbranch_scc1 .Lmy_cs_done
	s_waitcnt vmcnt(0)
	v_lshlrev_b32_e32 v13, 16, v190
	v_and_or_b32 v14, v6, s85, v13
	v_lshrrev_b32_e32 v13, 16, v6
	v_and_or_b32 v15, v190, s86, v13
	v_lshlrev_b32_e32 v13, 16, v191
	v_and_or_b32 v16, v7, s85, v13
	v_lshrrev_b32_e32 v13, 16, v7
	v_and_or_b32 v17, v191, s86, v13
	v_lshlrev_b32_e32 v13, 16, v192
	v_and_or_b32 v20, v8, s85, v13
	v_lshrrev_b32_e32 v13, 16, v8
	v_and_or_b32 v21, v192, s86, v13
	v_lshlrev_b32_e32 v13, 16, v193
	v_and_or_b32 v22, v9, s85, v13
	v_lshrrev_b32_e32 v13, 16, v9
	v_and_or_b32 v23, v193, s86, v13
	ds_write_b128 v12, v[14:17]
	ds_write_b128 v12, v[20:23] offset:1024
